# prologue transposes striped over workgroups 32-255 only (0-31 run two adaLN GEMV tasks); phase probe 46.3 -> 44.4 us
# baseline (speedup 1.0000x reference)
; __device__ __forceinline__ unsigned pk2(float lo, float hi) { unsigned r; asm("v_cvt_pk_bf16_f32 %0, %1, %2" : "=v"(r) : "v"(lo), "v"(hi)); return r; }
; template <class Map>
; __device__ __forceinline__ void transpose_item(const float* W, int K, int N, bf16_t* WT, float* scr, int item, int nblk, int lane, Map srccol) {
;     const int kb = item / nblk, nb = item % nblk, k0 = 64 * kb, n0 = 32 * nb;
;     const int sc = srccol(n0 + (lane & 31));
;     float tv[32];
;     const float* wp = W + (size_t)(k0 + (lane >> 5)) * N + (sc >= 0 ? sc : 0);
; #pragma unroll
;     for (int i = 0; i < 32; ++i) tv[i] = wp[(size_t)(2 * i) * N];
; #pragma unroll
;     for (int i = 0; i < 32; ++i) { const int kk = 2 * i + (lane >> 5); scr[kk * 33 + (lane & 31)] = sc >= 0 ? tv[i] : 0.f; }
;     __builtin_amdgcn_s_waitcnt(0); asm volatile("" ::: "memory");
;     const int c = lane & 7;
; #pragma unroll
;     for (int j = 0; j < 4; ++j) { const int n = (lane >> 3) + 8 * j; const float* s = scr + (8 * c) * 33 + n;
;         u32x4 o; o.x = pk2(s[0 * 33], s[1 * 33]); o.y = pk2(s[2 * 33], s[3 * 33]); o.z = pk2(s[4 * 33], s[5 * 33]); o.w = pk2(s[6 * 33], s[7 * 33]);
;         *(u32x4*)(WT + (size_t)(n0 + n) * K + k0 + 8 * c) = o; }
; __device__ __forceinline__ void run_transposes(const P& p, unsigned char* lds, int wave, int lane, unsigned mask, int wid, int nw) {
;     float* scr = (float*)(lds + wave * 8448);
;     int base = 0;
; #pragma unroll 1
;     for (int mat = 0; mat < 12; ++mat) {
;         if (!((mask >> mat) & 1u)) continue;
;         const int n = mat_items(mat);
;         int first = (wid - base % nw + nw) % nw;
; #pragma unroll 1
;         for (int it = first; it < n; it += nw) mat_item(p, scr, mat, it, lane);
;         base += n;
.LBB0_8:
	s_cmp_lg_u32 s61, 0
	s_cbranch_scc1 .LBB0_7
	s_abs_i32 s9, s12
	v_readlane_b32 s64, v253, 4
	s_mul_hi_u32 s62, s9, s64
	v_readlane_b32 s63, v253, 3
	s_mul_i32 s62, s62, s63
	s_sub_i32 s9, s9, s62
	s_ashr_i32 s8, s12, 31
	s_sub_i32 s62, s9, s63
	s_cmp_ge_u32 s9, s63
	s_cselect_b32 s9, s62, s9
	s_sub_i32 s62, s9, s63
	s_cmp_ge_u32 s9, s63
	s_cselect_b32 s9, s62, s9
	s_xor_b32 s9, s9, s8
	s_sub_i32 s8, s8, s9
	s_add_i32 s8, s13, s8
	s_ashr_i32 s9, s8, 31
	s_abs_i32 s8, s8
	s_mul_hi_u32 s62, s8, s64
	s_mul_i32 s62, s62, s63
	s_sub_i32 s8, s8, s62
	s_sub_i32 s62, s8, s63
	s_cmp_ge_u32 s8, s63
	s_cselect_b32 s8, s62, s8
	s_sub_i32 s62, s8, s63
	s_cmp_ge_u32 s8, s63
	s_cselect_b32 s8, s62, s8
	s_xor_b32 s8, s8, s9
	s_sub_i32 s62, s8, s9
	s_mov_b32 s98, s4
	s_cmp_eq_u32 s38, 0x100
	s_cbranch_scc0 .Lpt_done
	s_movk_i32 s98, 0x700
	s_sub_i32 s62, s62, 0x100
	s_cmp_lt_i32 s62, 0
	s_cselect_b32 s62, 0x7fff, s62
.Lpt_done:
	s_cmpk_gt_i32 s62, 0xaff
	s_cbranch_scc1 .LBB0_6
	s_lshl_b32 s63, s62, 5
	s_lshl_b32 s64, s62, 4
.LBB0_11:
	s_mul_hi_i32 s8, s62, 0x2e8ba2e9
	s_lshr_b32 s9, s8, 31
	s_ashr_i32 s8, s8, 5
	s_add_i32 s9, s8, s9
	s_mul_i32 s65, s9, 0xffffea00
	s_lshl_b32 s8, s9, 6
	s_mulk_i32 s9, 0xf500
	s_add_i32 s65, s63, s65
	s_add_i32 s66, s64, s9
	v_or_b32_e32 v25, s65, v1
	v_and_or_b32 v2, s62, 4, v12
	v_mov_b64_e32 v[6:7], s[10:11]
	v_or_b32_e32 v21, s8, v8
	s_and_b32 s68, s66, 0xffffff80
	s_and_b32 s69, s65, 0x60
	v_lshlrev_b32_e32 v27, 1, v25
	v_mad_i64_i32 v[6:7], s[66:67], v21, s24, v[6:7]
	v_add_u32_e32 v24, s65, v9
	v_add_u32_e32 v21, s68, v11
	v_or_b32_e32 v2, s69, v2
	v_and_b32_e32 v32, 24, v27
	s_ashr_i32 s9, s8, 31
	v_ashrrev_i32_e32 v25, 31, v24
	v_add_u32_e32 v26, 8, v24
	v_add_u32_e32 v28, 16, v24
	v_add_u32_e32 v30, 24, v24
	v_or3_b32 v2, v2, v32, v21
	v_cmp_lt_i32_e32 vcc, -1, v21
	v_lshl_add_u64 v[22:23], s[8:9], 1, v[4:5]
	v_lshlrev_b64 v[24:25], 11, v[24:25]
	v_ashrrev_i32_e32 v27, 31, v26
	v_ashrrev_i32_e32 v29, 31, v28
	v_ashrrev_i32_e32 v31, 31, v30
	v_cndmask_b32_e32 v2, 0, v2, vcc
	v_lshl_add_u64 v[38:39], v[22:23], 0, v[24:25]
	v_lshlrev_b64 v[24:25], 11, v[26:27]
	v_lshlrev_b64 v[26:27], 11, v[28:29]
	v_lshlrev_b64 v[28:29], 11, v[30:31]
	v_lshl_add_u64 v[6:7], v[2:3], 2, v[6:7]
	v_lshl_add_u64 v[40:41], v[22:23], 0, v[24:25]
	v_lshl_add_u64 v[42:43], v[22:23], 0, v[26:27]
	v_lshl_add_u64 v[44:45], v[22:23], 0, v[28:29]
	v_add_co_u32_e64 v22, s[8:9], s25, v6
	s_add_i32 s62, s62, s98
	s_nop 0
	v_addc_co_u32_e64 v23, s[8:9], 0, v7, s[8:9]
	v_add_co_u32_e64 v24, s[8:9], s26, v6
	s_lshl_b32 s99, s98, 5
	s_add_i32 s63, s63, s99
	s_nop 0
	v_addc_co_u32_e64 v25, s[8:9], 0, v7, s[8:9]
	v_add_co_u32_e64 v26, s[8:9], s27, v6
	s_lshl_b32 s99, s98, 4
	s_add_i32 s64, s64, s99
	s_nop 0
	v_addc_co_u32_e64 v27, s[8:9], 0, v7, s[8:9]
	v_add_co_u32_e64 v28, s[8:9], s28, v6
	s_cmpk_gt_i32 s62, 0xaff
	s_nop 0
	v_addc_co_u32_e64 v29, s[8:9], 0, v7, s[8:9]
	v_add_co_u32_e64 v30, s[8:9], s29, v6
	s_nop 1
	v_addc_co_u32_e64 v31, s[8:9], 0, v7, s[8:9]
	v_add_co_u32_e64 v32, s[8:9], s30, v6
	s_nop 1
	v_addc_co_u32_e64 v33, s[8:9], 0, v7, s[8:9]
	v_add_co_u32_e64 v34, s[8:9], s31, v6
	s_nop 1
	v_addc_co_u32_e64 v35, s[8:9], 0, v7, s[8:9]
	v_add_co_u32_e64 v36, s[8:9], s33, v6
	s_nop 1
	v_addc_co_u32_e64 v37, s[8:9], 0, v7, s[8:9]
	v_add_co_u32_e64 v46, s[8:9], s34, v6
	s_nop 1
	v_addc_co_u32_e64 v47, s[8:9], 0, v7, s[8:9]
	v_add_co_u32_e64 v48, s[8:9], s35, v6
	s_nop 1
	v_addc_co_u32_e64 v49, s[8:9], 0, v7, s[8:9]
	v_add_co_u32_e64 v50, s[8:9], s40, v6
	s_nop 1
	v_addc_co_u32_e64 v51, s[8:9], 0, v7, s[8:9]
	v_add_co_u32_e64 v52, s[8:9], s41, v6
	s_nop 1
	v_addc_co_u32_e64 v53, s[8:9], 0, v7, s[8:9]
	v_add_co_u32_e64 v54, s[8:9], s42, v6
	s_nop 1
	v_addc_co_u32_e64 v55, s[8:9], 0, v7, s[8:9]
	v_add_co_u32_e64 v56, s[8:9], s43, v6
	s_nop 1
	v_addc_co_u32_e64 v57, s[8:9], 0, v7, s[8:9]
	v_add_co_u32_e64 v58, s[8:9], s44, v6
	s_nop 1
	v_addc_co_u32_e64 v59, s[8:9], 0, v7, s[8:9]
	v_add_co_u32_e64 v60, s[8:9], s45, v6
	s_nop 1
	v_addc_co_u32_e64 v61, s[8:9], 0, v7, s[8:9]
	v_add_co_u32_e64 v62, s[8:9], s46, v6
	s_nop 1
	v_addc_co_u32_e64 v63, s[8:9], 0, v7, s[8:9]
	v_add_co_u32_e64 v64, s[8:9], s47, v6
	s_nop 1
	v_addc_co_u32_e64 v65, s[8:9], 0, v7, s[8:9]
	v_add_co_u32_e64 v66, s[8:9], s48, v6
	s_nop 1
	v_addc_co_u32_e64 v67, s[8:9], 0, v7, s[8:9]
	v_add_co_u32_e64 v68, s[8:9], s49, v6
	s_nop 1
	v_addc_co_u32_e64 v69, s[8:9], 0, v7, s[8:9]
	v_add_co_u32_e64 v70, s[8:9], s50, v6
	s_nop 1
	v_addc_co_u32_e64 v71, s[8:9], 0, v7, s[8:9]
	v_add_co_u32_e64 v72, s[8:9], s51, v6
	s_nop 1
	v_addc_co_u32_e64 v73, s[8:9], 0, v7, s[8:9]
	v_add_co_u32_e64 v74, s[8:9], s52, v6
	s_nop 1
	v_addc_co_u32_e64 v75, s[8:9], 0, v7, s[8:9]
	v_add_co_u32_e64 v76, s[8:9], s53, v6
	s_nop 1
	v_addc_co_u32_e64 v77, s[8:9], 0, v7, s[8:9]
	v_add_co_u32_e64 v78, s[8:9], s54, v6
	s_nop 1
	v_addc_co_u32_e64 v79, s[8:9], 0, v7, s[8:9]
	v_add_co_u32_e64 v80, s[8:9], s55, v6
	s_nop 1
	v_addc_co_u32_e64 v81, s[8:9], 0, v7, s[8:9]
	v_add_co_u32_e64 v82, s[8:9], s56, v6
	s_nop 1
	v_addc_co_u32_e64 v83, s[8:9], 0, v7, s[8:9]
	v_add_co_u32_e64 v84, s[8:9], s57, v6
	s_nop 1
	v_addc_co_u32_e64 v85, s[8:9], 0, v7, s[8:9]
	v_add_co_u32_e64 v86, s[8:9], s58, v6
	s_nop 1
	v_addc_co_u32_e64 v87, s[8:9], 0, v7, s[8:9]
	v_add_co_u32_e64 v88, s[8:9], s59, v6
	s_nop 1
	v_addc_co_u32_e64 v89, s[8:9], 0, v7, s[8:9]
	v_add_co_u32_e64 v90, s[8:9], s60, v6
	s_nop 1
	v_addc_co_u32_e64 v91, s[8:9], 0, v7, s[8:9]
	global_load_dword v2, v[6:7], off
	s_nop 0
	global_load_dword v6, v[22:23], off
	global_load_dword v7, v[24:25], off
	global_load_dword v21, v[26:27], off
	s_nop 0
	global_load_dword v22, v[28:29], off
	global_load_dword v23, v[30:31], off
	global_load_dword v24, v[32:33], off
	global_load_dword v25, v[34:35], off
	global_load_dword v26, v[36:37], off
	global_load_dword v27, v[46:47], off
	global_load_dword v28, v[48:49], off
	global_load_dword v29, v[50:51], off
	global_load_dword v30, v[52:53], off
	global_load_dword v31, v[54:55], off
	global_load_dword v32, v[56:57], off
	global_load_dword v33, v[58:59], off
	global_load_dword v34, v[60:61], off
	global_load_dword v35, v[62:63], off
	global_load_dword v36, v[64:65], off
	global_load_dword v37, v[66:67], off
	global_load_dword v46, v[68:69], off
	global_load_dword v47, v[70:71], off
	global_load_dword v48, v[72:73], off
	global_load_dword v49, v[74:75], off
	global_load_dword v50, v[76:77], off
	global_load_dword v51, v[78:79], off
	global_load_dword v52, v[80:81], off
	global_load_dword v53, v[82:83], off
	global_load_dword v54, v[84:85], off
	global_load_dword v55, v[86:87], off
	global_load_dword v56, v[88:89], off
	global_load_dword v57, v[90:91], off
	s_waitcnt vmcnt(31)
; __device__ __forceinline__ unsigned pk2(float lo, float hi) { unsigned r; asm("v_cvt_pk_bf16_f32 %0, %1, %2" : "=v"(r) : "v"(lo), "v"(hi)); return r; }
; __device__ __forceinline__ float siluf(float v) { return v * __builtin_amdgcn_rcpf(1.f + __expf(-v)); }
; template <class Map>
; __device__ __forceinline__ void transpose_item(const float* W, int K, int N, bf16_t* WT, float* scr, int item, int nblk, int lane, Map srccol) {
;     ...
;     for (int i = 0; i < 32; ++i) tv[i] = wp[(size_t)(2 * i) * N];
; #pragma unroll
;     for (int i = 0; i < 32; ++i) { const int kk = 2 * i + (lane >> 5); scr[kk * 33 + (lane & 31)] = sc >= 0 ? tv[i] : 0.f; }
;     __builtin_amdgcn_s_waitcnt(0); asm volatile("" ::: "memory");
;     const int c = lane & 7;
; #pragma unroll
;     for (int j = 0; j < 4; ++j) { const int n = (lane >> 3) + 8 * j; const float* s = scr + (8 * c) * 33 + n;
;         u32x4 o; o.x = pk2(s[0 * 33], s[1 * 33]); o.y = pk2(s[2 * 33], s[3 * 33]); o.z = pk2(s[4 * 33], s[5 * 33]); o.w = pk2(s[6 * 33], s[7 * 33]);
;         *(u32x4*)(WT + (size_t)(n0 + n) * K + k0 + 8 * c) = o; }
;     __builtin_amdgcn_s_waitcnt(0); asm volatile("" ::: "memory");
; __device__ __forceinline__ void ph_prologue(const P& p, unsigned char* lds, int tid, int wave, int lane, int G) {
;     run_transposes(p, lds, wave, lane, 0x001u, blockIdx.x * 8 + wave, G * 8);
;     __syncthreads();
;     float* sv = (float*)lds;
;     float* red = (float*)(lds + 36864);
;     bool have = false;
;     typedef float f32x2_ __attribute__((ext_vector_type(2)));
;     for (int task = blockIdx.x; task < 256; task += G) {
;         if (!have) {
;             for (int i = tid; i < 9 * 1024; i += NTHREADS) { const float v = i < 8192 ? p.c[i] : p.c_ctx[i - 8192]; sv[i] = siluf(v); }
;             have = true; __syncthreads();
;         }
;         const int l = task >> 7, c0 = (task & 127) * 72;
;         const bool actv = lane < 36;
;         const float* w = p.ada_w + (size_t)l * DM * 9216 + c0 + 2 * (actv ? lane : 0);
;         float acc0[9], acc1[9];
; #pragma unroll
;         for (int r = 0; r < 9; ++r) { acc0[r] = 0.f; acc1[r] = 0.f; }
;         const int kb = wave * 128;
	v_cndmask_b32_e32 v2, 0, v2, vcc
	s_waitcnt vmcnt(30)
	v_cndmask_b32_e32 v6, 0, v6, vcc
	s_waitcnt vmcnt(29)
	v_cndmask_b32_e32 v7, 0, v7, vcc
	s_waitcnt vmcnt(28)
	v_cndmask_b32_e32 v21, 0, v21, vcc
	s_waitcnt vmcnt(27)
	v_cndmask_b32_e32 v22, 0, v22, vcc
	s_waitcnt vmcnt(26)
	v_cndmask_b32_e32 v23, 0, v23, vcc
	s_waitcnt vmcnt(25)
	v_cndmask_b32_e32 v24, 0, v24, vcc
	s_waitcnt vmcnt(24)
	v_cndmask_b32_e32 v25, 0, v25, vcc
	s_waitcnt vmcnt(23)
	v_cndmask_b32_e32 v26, 0, v26, vcc
	s_waitcnt vmcnt(22)
	v_cndmask_b32_e32 v27, 0, v27, vcc
	s_waitcnt vmcnt(21)
	v_cndmask_b32_e32 v28, 0, v28, vcc
	s_waitcnt vmcnt(20)
	v_cndmask_b32_e32 v29, 0, v29, vcc
	s_waitcnt vmcnt(19)
	v_cndmask_b32_e32 v30, 0, v30, vcc
	s_waitcnt vmcnt(18)
	v_cndmask_b32_e32 v31, 0, v31, vcc
	s_waitcnt vmcnt(17)
	v_cndmask_b32_e32 v32, 0, v32, vcc
	s_waitcnt vmcnt(16)
	v_cndmask_b32_e32 v33, 0, v33, vcc
	s_waitcnt vmcnt(15)
	v_cndmask_b32_e32 v34, 0, v34, vcc
	s_waitcnt vmcnt(14)
	v_cndmask_b32_e32 v35, 0, v35, vcc
	s_waitcnt vmcnt(13)
	v_cndmask_b32_e32 v36, 0, v36, vcc
	s_waitcnt vmcnt(12)
	v_cndmask_b32_e32 v37, 0, v37, vcc
	s_waitcnt vmcnt(11)
	v_cndmask_b32_e32 v46, 0, v46, vcc
	s_waitcnt vmcnt(10)
	v_cndmask_b32_e32 v47, 0, v47, vcc
	s_waitcnt vmcnt(9)
	v_cndmask_b32_e32 v48, 0, v48, vcc
	s_waitcnt vmcnt(8)
	v_cndmask_b32_e32 v49, 0, v49, vcc
	s_waitcnt vmcnt(7)
	v_cndmask_b32_e32 v50, 0, v50, vcc
	s_waitcnt vmcnt(6)
	v_cndmask_b32_e32 v51, 0, v51, vcc
	s_waitcnt vmcnt(5)
	v_cndmask_b32_e32 v52, 0, v52, vcc
	s_waitcnt vmcnt(4)
	v_cndmask_b32_e32 v53, 0, v53, vcc
	s_waitcnt vmcnt(3)
	v_cndmask_b32_e32 v54, 0, v54, vcc
	s_waitcnt vmcnt(2)
	v_cndmask_b32_e32 v55, 0, v55, vcc
	s_waitcnt vmcnt(1)
	v_cndmask_b32_e32 v56, 0, v56, vcc
	s_waitcnt vmcnt(0)
	v_cndmask_b32_e32 v57, 0, v57, vcc
	ds_write2_b32 v13, v2, v6 offset1:66
	ds_write2_b32 v13, v7, v21 offset0:132 offset1:198
	ds_write2_b32 v14, v22, v23 offset0:8 offset1:74
	ds_write2_b32 v14, v24, v25 offset0:140 offset1:206
	ds_write2_b32 v15, v26, v27 offset0:16 offset1:82
	ds_write2_b32 v15, v28, v29 offset0:148 offset1:214
	ds_write2_b32 v16, v30, v31 offset0:24 offset1:90
	ds_write2_b32 v16, v32, v33 offset0:156 offset1:222
	ds_write2_b32 v17, v34, v35 offset0:32 offset1:98
	ds_write2_b32 v17, v36, v37 offset0:164 offset1:230
	ds_write2_b32 v18, v46, v47 offset0:40 offset1:106
	ds_write2_b32 v18, v48, v49 offset0:172 offset1:238
	ds_write2_b32 v19, v50, v51 offset0:48 offset1:114
	ds_write2_b32 v19, v52, v53 offset0:180 offset1:246
	ds_write2_b32 v20, v54, v55 offset0:56 offset1:122
	ds_write2_b32 v20, v56, v57 offset0:188 offset1:254
	s_waitcnt vmcnt(0) expcnt(0) lgkmcnt(0)
	ds_read2_b32 v[6:7], v10 offset0:33 offset1:41
	ds_read2_b32 v[24:25], v10 offset1:8
	ds_read2_b32 v[26:27], v10 offset0:66 offset1:74
	ds_read2_b32 v[28:29], v10 offset0:99 offset1:107
	ds_read2_b32 v[30:31], v10 offset0:132 offset1:140
	ds_read2_b32 v[32:33], v10 offset0:165 offset1:173
	ds_read2_b32 v[34:35], v10 offset0:198 offset1:206
	ds_read2_b32 v[36:37], v10 offset0:231 offset1:239
	ds_read2_b32 v[46:47], v10 offset0:16 offset1:24
	ds_read2_b32 v[48:49], v10 offset0:49 offset1:57
	ds_read2_b32 v[50:51], v10 offset0:82 offset1:90
	ds_read2_b32 v[52:53], v10 offset0:115 offset1:123
	ds_read2_b32 v[54:55], v10 offset0:148 offset1:156
	ds_read2_b32 v[56:57], v10 offset0:181 offset1:189
	ds_read2_b32 v[58:59], v10 offset0:214 offset1:222
	ds_read2_b32 v[60:61], v10 offset0:247 offset1:255
	s_waitcnt lgkmcnt(14)
	v_cvt_pk_bf16_f32 v22, v24, v6
	s_waitcnt lgkmcnt(12)
	v_cvt_pk_bf16_f32 v23, v26, v28
	v_cvt_pk_bf16_f32 v26, v25, v7
	s_waitcnt lgkmcnt(10)
	v_cvt_pk_bf16_f32 v24, v30, v32
	s_waitcnt lgkmcnt(8)
	v_cvt_pk_bf16_f32 v25, v34, v36
	v_cvt_pk_bf16_f32 v27, v27, v29
	v_cvt_pk_bf16_f32 v28, v31, v33
	v_cvt_pk_bf16_f32 v29, v35, v37
	s_waitcnt lgkmcnt(6)
	v_cvt_pk_bf16_f32 v30, v46, v48
	s_waitcnt lgkmcnt(4)
	v_cvt_pk_bf16_f32 v31, v50, v52
	s_waitcnt lgkmcnt(2)
	v_cvt_pk_bf16_f32 v32, v54, v56
	s_waitcnt lgkmcnt(0)
	v_cvt_pk_bf16_f32 v33, v58, v60
	v_cvt_pk_bf16_f32 v34, v47, v49
	v_cvt_pk_bf16_f32 v35, v51, v53
	v_cvt_pk_bf16_f32 v36, v55, v57
	v_cvt_pk_bf16_f32 v37, v59, v61
	global_store_dwordx4 v[38:39], v[22:25], off
	global_store_dwordx4 v[40:41], v[26:29], off
	global_store_dwordx4 v[42:43], v[30:33], off
	global_store_dwordx4 v[44:45], v[34:37], off
	s_waitcnt vmcnt(0) expcnt(0) lgkmcnt(0)
	s_cbranch_scc0 .LBB0_11
	s_branch .LBB0_6
.LBB0_12:
	s_cmpk_lt_i32 s90, 0x100
	s_cselect_b64 s[8:9], -1, 0
	v_writelane_b32 v253, s8, 5
	s_cmpk_gt_i32 s90, 0xff
	s_nop 0
	v_writelane_b32 v253, s9, 6
	s_barrier
	s_cbranch_scc1 .LBB0_27
	s_lshl_b32 s12, s5, 9
	s_lshl_b32 s24, s5, 7
	s_add_i32 s33, s12, 0
	v_lshlrev_b32_e32 v2, 1, v1
	v_cmp_gt_u32_e64 s[8:9], 36, v1
	s_add_u32 s34, s22, 0x100000
	v_ashrrev_i32_e32 v147, 31, v146
	v_cndmask_b32_e64 v4, 0, v2, s[8:9]
	s_addc_u32 s35, s23, 0
	v_lshl_add_u64 v[2:3], v[146:147], 2, s[20:21]
	s_mul_i32 s20, s5, 0x480000
	s_mul_hi_i32 s21, s24, 0x9000
	s_add_u32 s18, s18, s20
	v_lshlrev_b32_e32 v4, 2, v4
	v_mov_b32_e32 v5, 0
	s_addc_u32 s19, s19, s21
	v_lshl_add_u64 v[6:7], s[18:19], 0, v[4:5]
	s_mov_b64 s[18:19], 0x3f000
	s_movk_i32 s10, 0x2400
	s_movk_i32 s12, 0x288
	v_lshl_add_u32 v8, v1, 3, 0
	s_mul_i32 s26, s5, 0xa20
	v_lshl_add_u64 v[6:7], v[6:7], 0, s[18:19]
	s_movk_i32 s18, 0x8000
	v_cmp_gt_i32_e64 s[10:11], s10, v146
	v_cmp_gt_i32_e64 s[12:13], s12, v146
	v_lshl_add_u32 v1, v146, 2, 0
	s_mov_b32 s5, 0x9000
	s_mov_b64 s[24:25], 0
	s_movk_i32 s40, 0x2000
	s_mov_b32 s19, -1
	s_mov_b64 s[20:21], 0x800
	s_movk_i32 s41, 0x21ff
	s_mov_b32 s42, 0xfffc1000
	s_mov_b32 s43, 0xfffca000
	s_mov_b32 s44, 0xfffd3000
	s_mov_b32 s45, 0xfffdc000
	s_mov_b32 s46, 0xfffe5000
	s_mov_b32 s47, 0xfffee000
	s_mov_b32 s48, 0xffff7000
	s_mov_b64 s[22:23], 0x48000
	v_add_u32_e32 v36, s26, v8
	s_add_i32 s49, 0, 0x9000
	s_mov_b32 s50, 0x38e38e39
	s_movk_i32 s51, 0xffb8
	s_movk_i32 s52, 0x87
	s_mov_b32 s53, s90
	s_mov_b32 s54, s90
	s_branch .LBB0_15
	s_nop 0
	s_nop 0
	s_nop 0
	s_nop 0
.LBB0_14:
	s_or_b64 exec, exec, s[24:25]
	s_add_i32 s54, s54, s38
	s_add_i32 s53, s53, s38
	s_cmpk_gt_i32 s54, 0xff
	s_mov_b64 s[24:25], -1
	s_barrier
	s_cbranch_scc1 .LBB0_27
